# code placement: P2 GEMM K-loop head moved from byte phase 4 mod 8 to 0 mod 8 (redundant branch-to-next removed, compensating s_nop after the loop)
# speedup vs baseline: 1.0034x; 1.0034x over previous
; template <bool SWAP, class Epi>
; DI void gemm_tile(const u16* __restrict__ A, int lda, const u16* __restrict__ Bt, int ldb, int K, int m0, int n0, char* smem, Epi&& epi) {
;     ...
;   for (int kt = 0; kt < KT; kt += 2) {
;     if (kt + 2 < KT) {
;       const int k0 = (kt + 2) << 6;
; #pragma unroll
;       for (int i = 0; i < 4; ++i) { ra0[i] = *(const u32x4*)(ag + (size_t)i * 32 * lda + k0); rb0[i] = *(const u32x4*)(bg + (size_t)i * 32 * ldb + k0); }
;     }
;     compute(0);
; #pragma unroll
;     for (int i = 0; i < 4; ++i) { *(u32x4*)(asw + 128 * 72 + 32 * i * 72) = ra1[i]; *(u32x4*)(bsw + 128 * 72 + 32 * i * 72) = rb1[i]; }
;     __syncthreads();
;     if (kt + 3 < KT) {
;       const int k0 = (kt + 3) << 6;
; #pragma unroll
;       for (int i = 0; i < 4; ++i) { ra1[i] = *(const u32x4*)(ag + (size_t)i * 32 * lda + k0); rb1[i] = *(const u32x4*)(bg + (size_t)i * 32 * ldb + k0); }
;     }
;     compute(1);
;     if (kt + 2 < KT) {
; #pragma unroll
;       for (int i = 0; i < 4; ++i) { *(u32x4*)(asw + 32 * i * 72) = ra0[i]; *(u32x4*)(bsw + 32 * i * 72) = rb0[i]; }
;     }
;     __syncthreads();
.LBB0_387:
	global_load_dwordx4 v[66:69], v194, s[100:101] offset:256
	global_load_dwordx4 v[70:73], v190, s[98:99] offset:256
	global_load_dwordx4 v[74:77], v195, s[100:101] offset:256
	global_load_dwordx4 v[78:81], v191, s[98:99] offset:256
	global_load_dwordx4 v[82:85], v196, s[100:101] offset:256
	global_load_dwordx4 v[86:89], v192, s[98:99] offset:256
	global_load_dwordx4 v[90:93], v197, s[100:101] offset:256
	global_load_dwordx4 v[94:97], v193, s[98:99] offset:256
	ds_read_b128 v[154:157], v149 offset:16
	ds_read_b128 v[158:161], v149 offset:48
	ds_read_b128 v[162:165], v149 offset:4624
	ds_read_b128 v[166:169], v149 offset:4656
	ds_read_b128 v[170:173], v150 offset:36880
	ds_read_b128 v[174:177], v150 offset:36912
	ds_read_b128 v[178:181], v150 offset:41488
	ds_read_b128 v[182:185], v150 offset:41520
	s_waitcnt lgkmcnt(3)
	v_mfma_f32_32x32x16_bf16 v[50:65], v[170:173], v[154:157], v[50:65]
	s_waitcnt lgkmcnt(1)
	v_mfma_f32_32x32x16_bf16 v[34:49], v[178:181], v[154:157], v[34:49]
	v_mfma_f32_32x32x16_bf16 v[18:33], v[170:173], v[162:165], v[18:33]
	v_mfma_f32_32x32x16_bf16 v[2:17], v[178:181], v[162:165], v[2:17]
	ds_read_b128 v[154:157], v149 offset:80
	ds_read_b128 v[162:165], v149 offset:4688
	ds_read_b128 v[170:173], v150 offset:36944
	ds_read_b128 v[178:181], v150 offset:41552
	v_mfma_f32_32x32x16_bf16 v[50:65], v[174:177], v[158:161], v[50:65]
	s_waitcnt lgkmcnt(4)
	v_mfma_f32_32x32x16_bf16 v[34:49], v[182:185], v[158:161], v[34:49]
	v_mfma_f32_32x32x16_bf16 v[18:33], v[174:177], v[166:169], v[18:33]
	v_mfma_f32_32x32x16_bf16 v[2:17], v[182:185], v[166:169], v[2:17]
	ds_read_b128 v[158:161], v149 offset:112
	ds_read_b128 v[166:169], v149 offset:4720
	ds_read_b128 v[174:177], v150 offset:36976
	ds_read_b128 v[182:185], v150 offset:41584
	s_waitcnt lgkmcnt(5)
	v_mfma_f32_32x32x16_bf16 v[50:65], v[170:173], v[154:157], v[50:65]
	s_waitcnt vmcnt(14)
	ds_write_b128 v146, v[98:101] offset:18448
	ds_write_b128 v146, v[102:105] offset:55312
	s_waitcnt lgkmcnt(6)
	v_mfma_f32_32x32x16_bf16 v[34:49], v[178:181], v[154:157], v[34:49]
	v_mfma_f32_32x32x16_bf16 v[18:33], v[170:173], v[162:165], v[18:33]
	s_waitcnt vmcnt(12)
	ds_write_b128 v146, v[106:109] offset:23056
	ds_write_b128 v146, v[110:113] offset:59920
	v_mfma_f32_32x32x16_bf16 v[2:17], v[178:181], v[162:165], v[2:17]
	s_waitcnt vmcnt(10)
	ds_write_b128 v146, v[114:117] offset:27664
	ds_write_b128 v146, v[118:121] offset:64528
	s_waitcnt lgkmcnt(7)
	v_mfma_f32_32x32x16_bf16 v[50:65], v[174:177], v[158:161], v[50:65]
	s_waitcnt vmcnt(8)
	ds_write_b128 v146, v[122:125] offset:32272
	ds_write_b128 v147, v[126:129] offset:32256
	s_waitcnt lgkmcnt(8)
	v_mfma_f32_32x32x16_bf16 v[34:49], v[182:185], v[158:161], v[34:49]
	v_mfma_f32_32x32x16_bf16 v[18:33], v[174:177], v[166:169], v[18:33]
	v_mfma_f32_32x32x16_bf16 v[2:17], v[182:185], v[166:169], v[2:17]
	s_waitcnt lgkmcnt(0)
	s_barrier
	global_load_dwordx4 v[98:101], v194, s[100:101] offset:384
	global_load_dwordx4 v[102:105], v190, s[98:99] offset:384
	global_load_dwordx4 v[106:109], v195, s[100:101] offset:384
	global_load_dwordx4 v[110:113], v191, s[98:99] offset:384
	global_load_dwordx4 v[114:117], v196, s[100:101] offset:384
	global_load_dwordx4 v[118:121], v192, s[98:99] offset:384
	global_load_dwordx4 v[122:125], v197, s[100:101] offset:384
	global_load_dwordx4 v[126:129], v193, s[98:99] offset:384
	ds_read_b128 v[142:145], v149 offset:18448
	ds_read_b128 v[154:157], v149 offset:18480
	ds_read_b128 v[158:161], v149 offset:23056
	ds_read_b128 v[162:165], v149 offset:23088
	ds_read_b128 v[166:169], v150 offset:55312
	ds_read_b128 v[170:173], v150 offset:55344
	ds_read_b128 v[174:177], v150 offset:59920
	ds_read_b128 v[178:181], v150 offset:59952
	s_waitcnt lgkmcnt(3)
	v_mfma_f32_32x32x16_bf16 v[50:65], v[166:169], v[142:145], v[50:65]
	s_waitcnt lgkmcnt(1)
	v_mfma_f32_32x32x16_bf16 v[34:49], v[174:177], v[142:145], v[34:49]
	v_mfma_f32_32x32x16_bf16 v[18:33], v[166:169], v[158:161], v[18:33]
	v_mfma_f32_32x32x16_bf16 v[2:17], v[174:177], v[158:161], v[2:17]
	ds_read_b128 v[142:145], v149 offset:18512
	ds_read_b128 v[158:161], v149 offset:23120
	ds_read_b128 v[166:169], v150 offset:55376
	ds_read_b128 v[174:177], v150 offset:59984
	v_mfma_f32_32x32x16_bf16 v[50:65], v[170:173], v[154:157], v[50:65]
	s_waitcnt lgkmcnt(4)
	v_mfma_f32_32x32x16_bf16 v[34:49], v[178:181], v[154:157], v[34:49]
	v_mfma_f32_32x32x16_bf16 v[18:33], v[170:173], v[162:165], v[18:33]
	v_mfma_f32_32x32x16_bf16 v[2:17], v[178:181], v[162:165], v[2:17]
	ds_read_b128 v[154:157], v149 offset:18544
	ds_read_b128 v[162:165], v149 offset:23152
	ds_read_b128 v[170:173], v150 offset:55408
	ds_read_b128 v[178:181], v150 offset:60016
	s_waitcnt lgkmcnt(5)
	v_mfma_f32_32x32x16_bf16 v[50:65], v[166:169], v[142:145], v[50:65]
	s_waitcnt vmcnt(14)
	ds_write_b128 v146, v[66:69] offset:16
	ds_write_b128 v146, v[70:73] offset:36880
	s_waitcnt lgkmcnt(6)
	v_mfma_f32_32x32x16_bf16 v[34:49], v[174:177], v[142:145], v[34:49]
	v_mfma_f32_32x32x16_bf16 v[18:33], v[166:169], v[158:161], v[18:33]
	s_waitcnt vmcnt(12)
	ds_write_b128 v146, v[74:77] offset:4624
	ds_write_b128 v146, v[78:81] offset:41488
	v_mfma_f32_32x32x16_bf16 v[2:17], v[174:177], v[158:161], v[2:17]
	s_waitcnt vmcnt(10)
	ds_write_b128 v146, v[82:85] offset:9232
	ds_write_b128 v146, v[86:89] offset:46096
	s_waitcnt lgkmcnt(7)
	v_mfma_f32_32x32x16_bf16 v[50:65], v[170:173], v[154:157], v[50:65]
	s_waitcnt vmcnt(8)
	ds_write_b128 v146, v[90:93] offset:13840
	ds_write_b128 v146, v[94:97] offset:50704
	s_waitcnt lgkmcnt(8)
	v_mfma_f32_32x32x16_bf16 v[34:49], v[178:181], v[154:157], v[34:49]
	v_mfma_f32_32x32x16_bf16 v[18:33], v[170:173], v[162:165], v[18:33]
	v_mfma_f32_32x32x16_bf16 v[2:17], v[178:181], v[162:165], v[2:17]
	s_add_i32 s24, s24, 2
	s_add_u32 s98, s98, 256
	s_addc_u32 s99, s99, 0
	s_add_u32 s100, s100, 256
	s_addc_u32 s101, s101, 0
	s_waitcnt lgkmcnt(0)
	s_barrier
; template <bool SWAP, class Epi>
; DI void gemm_tile(const u16* __restrict__ A, int lda, const u16* __restrict__ Bt, int ldb, int K, int m0, int n0, char* smem, Epi&& epi) {
;     ...
;   for (int kt = 0; kt < KT; kt += 2) {
;     if (kt + 2 < KT) {
;       const int k0 = (kt + 2) << 6;
; #pragma unroll
;       for (int i = 0; i < 4; ++i) { ra0[i] = *(const u32x4*)(ag + (size_t)i * 32 * lda + k0); rb0[i] = *(const u32x4*)(bg + (size_t)i * 32 * ldb + k0); }
;     }
;     compute(0);
; #pragma unroll
;     for (int i = 0; i < 4; ++i) { *(u32x4*)(asw + 128 * 72 + 32 * i * 72) = ra1[i]; *(u32x4*)(bsw + 128 * 72 + 32 * i * 72) = rb1[i]; }
;     __syncthreads();
;     if (kt + 3 < KT) {
;       const int k0 = (kt + 3) << 6;
; #pragma unroll
;       for (int i = 0; i < 4; ++i) { ra1[i] = *(const u32x4*)(ag + (size_t)i * 32 * lda + k0); rb1[i] = *(const u32x4*)(bg + (size_t)i * 32 * ldb + k0); }
;     }
;     compute(1);
;     if (kt + 2 < KT) {
; #pragma unroll
;       for (int i = 0; i < 4; ++i) { *(u32x4*)(asw + 32 * i * 72) = ra0[i]; *(u32x4*)(bsw + 32 * i * 72) = rb0[i]; }
;     }
;     __syncthreads();
;   }
	s_cmp_lt_u32 s24, 30
	s_cbranch_scc1 .LBB0_387
	ds_read_b128 v[154:157], v149 offset:16
	ds_read_b128 v[158:161], v149 offset:48
	ds_read_b128 v[162:165], v149 offset:4624
	ds_read_b128 v[166:169], v149 offset:4656
	ds_read_b128 v[170:173], v150 offset:36880
	ds_read_b128 v[174:177], v150 offset:36912
	ds_read_b128 v[178:181], v150 offset:41488
	ds_read_b128 v[182:185], v150 offset:41520
	s_waitcnt lgkmcnt(3)
	v_mfma_f32_32x32x16_bf16 v[50:65], v[170:173], v[154:157], v[50:65]
	s_waitcnt lgkmcnt(1)
	v_mfma_f32_32x32x16_bf16 v[34:49], v[178:181], v[154:157], v[34:49]
	v_mfma_f32_32x32x16_bf16 v[18:33], v[170:173], v[162:165], v[18:33]
	v_mfma_f32_32x32x16_bf16 v[2:17], v[178:181], v[162:165], v[2:17]
	ds_read_b128 v[154:157], v149 offset:80
	ds_read_b128 v[162:165], v149 offset:4688
	ds_read_b128 v[170:173], v150 offset:36944
	ds_read_b128 v[178:181], v150 offset:41552
	v_mfma_f32_32x32x16_bf16 v[50:65], v[174:177], v[158:161], v[50:65]
	s_waitcnt lgkmcnt(4)
	v_mfma_f32_32x32x16_bf16 v[34:49], v[182:185], v[158:161], v[34:49]
	v_mfma_f32_32x32x16_bf16 v[18:33], v[174:177], v[166:169], v[18:33]
	v_mfma_f32_32x32x16_bf16 v[2:17], v[182:185], v[166:169], v[2:17]
	ds_read_b128 v[158:161], v149 offset:112
	ds_read_b128 v[166:169], v149 offset:4720
	ds_read_b128 v[174:177], v150 offset:36976
	ds_read_b128 v[182:185], v150 offset:41584
	s_waitcnt lgkmcnt(5)
	v_mfma_f32_32x32x16_bf16 v[50:65], v[170:173], v[154:157], v[50:65]
	s_waitcnt vmcnt(6)
	ds_write_b128 v146, v[98:101] offset:18448
	ds_write_b128 v146, v[102:105] offset:55312
	s_waitcnt lgkmcnt(6)
	v_mfma_f32_32x32x16_bf16 v[34:49], v[178:181], v[154:157], v[34:49]
	v_mfma_f32_32x32x16_bf16 v[18:33], v[170:173], v[162:165], v[18:33]
	s_waitcnt vmcnt(4)
	ds_write_b128 v146, v[106:109] offset:23056
	ds_write_b128 v146, v[110:113] offset:59920
	v_mfma_f32_32x32x16_bf16 v[2:17], v[178:181], v[162:165], v[2:17]
	s_waitcnt vmcnt(2)
	ds_write_b128 v146, v[114:117] offset:27664
	ds_write_b128 v146, v[118:121] offset:64528
	s_waitcnt lgkmcnt(7)
	v_mfma_f32_32x32x16_bf16 v[50:65], v[174:177], v[158:161], v[50:65]
	s_waitcnt vmcnt(0)
	ds_write_b128 v146, v[122:125] offset:32272
	ds_write_b128 v147, v[126:129] offset:32256
	s_waitcnt lgkmcnt(8)
	v_mfma_f32_32x32x16_bf16 v[34:49], v[182:185], v[158:161], v[34:49]
	v_mfma_f32_32x32x16_bf16 v[18:33], v[174:177], v[166:169], v[18:33]
	v_mfma_f32_32x32x16_bf16 v[2:17], v[182:185], v[166:169], v[2:17]
	s_waitcnt lgkmcnt(0)
	s_barrier
	ds_read_b128 v[142:145], v149 offset:18448
	ds_read_b128 v[154:157], v149 offset:18480
	ds_read_b128 v[158:161], v149 offset:23056
	ds_read_b128 v[162:165], v149 offset:23088
	ds_read_b128 v[166:169], v150 offset:55312
	ds_read_b128 v[170:173], v150 offset:55344
	ds_read_b128 v[174:177], v150 offset:59920
	ds_read_b128 v[178:181], v150 offset:59952
	s_waitcnt lgkmcnt(3)
	v_mfma_f32_32x32x16_bf16 v[50:65], v[166:169], v[142:145], v[50:65]
	s_waitcnt lgkmcnt(1)
	v_mfma_f32_32x32x16_bf16 v[34:49], v[174:177], v[142:145], v[34:49]
	v_mfma_f32_32x32x16_bf16 v[18:33], v[166:169], v[158:161], v[18:33]
	v_mfma_f32_32x32x16_bf16 v[2:17], v[174:177], v[158:161], v[2:17]
	ds_read_b128 v[142:145], v149 offset:18512
	ds_read_b128 v[158:161], v149 offset:23120
	ds_read_b128 v[166:169], v150 offset:55376
	ds_read_b128 v[174:177], v150 offset:59984
	v_mfma_f32_32x32x16_bf16 v[50:65], v[170:173], v[154:157], v[50:65]
	s_waitcnt lgkmcnt(4)
	v_mfma_f32_32x32x16_bf16 v[34:49], v[178:181], v[154:157], v[34:49]
	v_mfma_f32_32x32x16_bf16 v[18:33], v[170:173], v[162:165], v[18:33]
	v_mfma_f32_32x32x16_bf16 v[2:17], v[178:181], v[162:165], v[2:17]
	ds_read_b128 v[154:157], v149 offset:18544
	ds_read_b128 v[162:165], v149 offset:23152
	ds_read_b128 v[170:173], v150 offset:55408
	ds_read_b128 v[178:181], v150 offset:60016
	s_waitcnt lgkmcnt(5)
	v_mfma_f32_32x32x16_bf16 v[50:65], v[166:169], v[142:145], v[50:65]
	s_waitcnt lgkmcnt(4)
	v_mfma_f32_32x32x16_bf16 v[34:49], v[174:177], v[142:145], v[34:49]
	v_mfma_f32_32x32x16_bf16 v[18:33], v[166:169], v[158:161], v[18:33]
	v_mfma_f32_32x32x16_bf16 v[2:17], v[174:177], v[158:161], v[2:17]
	s_waitcnt lgkmcnt(1)
	v_mfma_f32_32x32x16_bf16 v[50:65], v[170:173], v[154:157], v[50:65]
	s_waitcnt lgkmcnt(0)
	v_mfma_f32_32x32x16_bf16 v[34:49], v[178:181], v[154:157], v[34:49]
	v_mfma_f32_32x32x16_bf16 v[18:33], v[170:173], v[162:165], v[18:33]
	v_mfma_f32_32x32x16_bf16 v[2:17], v[178:181], v[162:165], v[2:17]
	s_waitcnt lgkmcnt(0)
	s_barrier
	s_nop 0
	s_branch .LBB0_393
